# attention P2/P3: 8-byte-per-lane output stores and partial loads widened to 16 bytes by pairing adjacent 16-lane rows with v_permlane16_swap_b32 (same bytes, same addresses)
# speedup vs baseline: 1.0229x; 1.0110x over previous
; template <int MODE, class Dec>
; __device__ __forceinline__ void attn_phase(const Frame& F, const bf16* Q, const bf16* K, const bf16* V, int nunits, const Dec dec, const bf16* O3, const float* L2, const float* L3) {
;     ...
;         bf16* op = cur.Og + qrow * (size_t)cur.ldo + h * 128 + 4 * g;
;         if (MODE == 1) { const bf16* o3p = O3 + qrow * 2048 + h * 128 + 4 * g;
; #pragma unroll
;             for (int dt = 0; dt < 8; ++dt) { a2[dt] = *(const v2u*)(op + 16 * dt); a3[dt] = *(const v2u*)(o3p + 16 * dt); }
;             l2v = L2[qrow * 16 + h]; l3v = L3[qrow * 16 + h]; }
;         if (has_next) { attn_issue<false>(F, K, nxt, 0);
;             q_load4(Q + (size_t)(nxt.b * SEQ + (nxt.n * 128 + qi) * nxt.d + nxt.r) * 2048 + nxt.h * 128 + 8 * g, qn); }
; #pragma unroll
;         for (int e = 0; e < 4; ++e) { if (4 * g + e < ql) s[0][e] = NEG; if (4 * g + e > ql) s[8][e] = NEG; }
;         if (n == 0) {
; #pragma unroll
;             for (int tt = 0; tt < 8; ++tt) { const bool dead = (w + tt < 8);
; #pragma unroll
;                 for (int e = 0; e < 4; ++e) s[tt][e] = dead ? NEG : s[tt][e]; } }
;         float mx = NEG;
; #pragma unroll
;         for (int tt = 0; tt < 9; ++tt) mx = fmaxf(fmaxf(mx, fmaxf(s[tt][0], s[tt][1])), fmaxf(s[tt][2], s[tt][3]));
;         mx = fmaxf(mx, __shfl_xor(mx, 16)); mx = fmaxf(mx, __shfl_xor(mx, 32));
;         float l = 0.f;
; #pragma unroll
;         for (int tt = 0; tt < 9; ++tt)
; #pragma unroll
;             for (int e = 0; e < 4; ++e) { const float p = __builtin_amdgcn_exp2f(s[tt][e] - mx); s[tt][e] = p; l += p; }
;         l += __shfl_xor(l, 16); l += __shfl_xor(l, 32);
;         bf16x8 pf[5];
; #pragma unroll
;         for (int pp = 0; pp < 5; ++pp) { const f32x4 px = s[2 * pp], py = (pp < 4) ? s[2 * pp + 1] : (f32x4){0.f, 0.f, 0.f, 0.f};
;             v4u u4; u4.x = pg8::cvt_pk_bf16(px[0], px[1]); u4.y = pg8::cvt_pk_bf16(px[2], px[3]); u4.z = pg8::cvt_pk_bf16(py[0], py[1]); u4.w = pg8::cvt_pk_bf16(py[2], py[3]);
;             pf[pp] = __builtin_bit_cast(bf16x8, u4); }
;         if (has_next) { if (nxt.n > 0) asm volatile("s_waitcnt vmcnt(12)" ::: "memory"); else asm volatile("s_waitcnt vmcnt(8)" ::: "memory"); }
;         else asm volatile("s_waitcnt vmcnt(0)" ::: "memory");
;         WG_BAR();
;         f32x4 o[8];
;         s16x4 vfa[10], vfb[10];
.LBB0_464:
	s_waitcnt lgkmcnt(0)
	v_add_f32_e32 v49, v36, v37
	s_lshl_b32 s60, s76, 11
	v_lshl_add_u32 v36, s75, 7, v87
	v_mul_lo_u32 v36, v36, s82
	s_add_i32 s60, s60, s57
	v_add_u32_e32 v44, s60, v36
	v_mad_u64_u32 v[36:37], s[64:65], v44, s73, 0
	v_ashrrev_i32_e32 v45, 31, v44
	v_mov_b32_e32 v38, v37
	v_mad_u64_u32 v[38:39], s[64:65], v45, s73, v[38:39]
	v_mov_b32_e32 v37, v38
	v_lshl_add_u64 v[36:37], v[36:37], 1, s[62:63]
	s_lshl_b32 s60, s56, 8
	v_lshl_add_u64 v[36:37], v[36:37], 0, s[60:61]
	s_waitcnt lgkmcnt(0)
	s_barrier
	v_lshl_add_u64 v[46:47], v[36:37], 0, v[62:63]
	ds_read_b64_tr_b16 v[112:113], v88
	ds_read_b64_tr_b16 v[114:115], v88 offset:4096
	ds_read_b64_tr_b16 v[108:109], v88 offset:8192
	ds_read_b64_tr_b16 v[110:111], v88 offset:12288
	ds_read_b64_tr_b16 v[104:105], v88 offset:16384
	ds_read_b64_tr_b16 v[106:107], v88 offset:20480
	ds_read_b64_tr_b16 v[40:41], v88 offset:24576
	ds_read_b64_tr_b16 v[42:43], v88 offset:28672
	ds_read_b64_tr_b16 v[36:37], v88 offset:32768
	ds_read_b64_tr_b16 v[38:39], v88 offset:32768
	ds_read_b64_tr_b16 v[132:133], v89
	ds_read_b64_tr_b16 v[134:135], v89 offset:4096
	ds_read_b64_tr_b16 v[128:129], v89 offset:8192
	ds_read_b64_tr_b16 v[130:131], v89 offset:12288
	ds_read_b64_tr_b16 v[124:125], v89 offset:16384
	ds_read_b64_tr_b16 v[126:127], v89 offset:20480
	ds_read_b64_tr_b16 v[120:121], v89 offset:24576
	ds_read_b64_tr_b16 v[122:123], v89 offset:28672
	ds_read_b64_tr_b16 v[116:117], v89 offset:32768
	ds_read_b64_tr_b16 v[118:119], v89 offset:32768
	s_nop 0
	s_waitcnt lgkmcnt(10)
	s_setprio 1
	v_mfma_f32_16x16x32_bf16 v[112:115], v[112:115], v[32:35], 0
	v_mfma_f32_16x16x32_bf16 v[108:111], v[108:111], v[28:31], v[112:115]
	v_mfma_f32_16x16x32_bf16 v[104:107], v[104:107], v[24:27], v[108:111]
	v_mfma_f32_16x16x32_bf16 v[40:43], v[40:43], v[20:23], v[104:107]
	v_mfma_f32_16x16x32_bf16 v[36:39], v[36:39], v[16:19], v[40:43]
	s_setprio 0
	ds_read_b64_tr_b16 v[140:141], v90
	ds_read_b64_tr_b16 v[142:143], v90 offset:4096
	ds_read_b64_tr_b16 v[136:137], v90 offset:8192
	ds_read_b64_tr_b16 v[138:139], v90 offset:12288
	ds_read_b64_tr_b16 v[112:113], v90 offset:16384
	ds_read_b64_tr_b16 v[114:115], v90 offset:20480
	ds_read_b64_tr_b16 v[108:109], v90 offset:24576
	ds_read_b64_tr_b16 v[110:111], v90 offset:28672
	ds_read_b64_tr_b16 v[104:105], v90 offset:32768
	ds_read_b64_tr_b16 v[106:107], v90 offset:32768
	s_waitcnt lgkmcnt(10)
	s_setprio 1
	v_mfma_f32_16x16x32_bf16 v[40:43], v[132:135], v[32:35], 0
	v_mfma_f32_16x16x32_bf16 v[40:43], v[128:131], v[28:31], v[40:43]
	v_mfma_f32_16x16x32_bf16 v[40:43], v[124:127], v[24:27], v[40:43]
	v_mfma_f32_16x16x32_bf16 v[40:43], v[120:123], v[20:23], v[40:43]
	v_mfma_f32_16x16x32_bf16 v[40:43], v[116:119], v[16:19], v[40:43]
	s_setprio 0
	ds_read_b64_tr_b16 v[132:133], v91
	ds_read_b64_tr_b16 v[134:135], v91 offset:4096
	ds_read_b64_tr_b16 v[128:129], v91 offset:8192
	ds_read_b64_tr_b16 v[130:131], v91 offset:12288
	ds_read_b64_tr_b16 v[124:125], v91 offset:16384
	ds_read_b64_tr_b16 v[126:127], v91 offset:20480
	ds_read_b64_tr_b16 v[120:121], v91 offset:24576
	ds_read_b64_tr_b16 v[122:123], v91 offset:28672
	ds_read_b64_tr_b16 v[116:117], v91 offset:32768
	ds_read_b64_tr_b16 v[118:119], v91 offset:32768
	s_waitcnt lgkmcnt(10)
	s_setprio 1
	v_mfma_f32_16x16x32_bf16 v[140:143], v[140:143], v[32:35], 0
	v_mfma_f32_16x16x32_bf16 v[136:139], v[136:139], v[28:31], v[140:143]
	v_mfma_f32_16x16x32_bf16 v[112:115], v[112:115], v[24:27], v[136:139]
	v_mfma_f32_16x16x32_bf16 v[108:111], v[108:111], v[20:23], v[112:115]
	v_mfma_f32_16x16x32_bf16 v[104:107], v[104:107], v[16:19], v[108:111]
	s_setprio 0
	ds_read_b64_tr_b16 v[144:145], v92
	ds_read_b64_tr_b16 v[146:147], v92 offset:4096
	ds_read_b64_tr_b16 v[140:141], v92 offset:8192
	ds_read_b64_tr_b16 v[142:143], v92 offset:12288
	ds_read_b64_tr_b16 v[136:137], v92 offset:16384
	ds_read_b64_tr_b16 v[138:139], v92 offset:20480
	ds_read_b64_tr_b16 v[112:113], v92 offset:24576
	ds_read_b64_tr_b16 v[114:115], v92 offset:28672
	ds_read_b64_tr_b16 v[108:109], v92 offset:32768
	ds_read_b64_tr_b16 v[110:111], v92 offset:32768
	s_waitcnt lgkmcnt(10)
	s_setprio 1
	v_mfma_f32_16x16x32_bf16 v[132:135], v[132:135], v[32:35], 0
	v_mfma_f32_16x16x32_bf16 v[128:131], v[128:131], v[28:31], v[132:135]
	v_mfma_f32_16x16x32_bf16 v[124:127], v[124:127], v[24:27], v[128:131]
	v_mfma_f32_16x16x32_bf16 v[120:123], v[120:123], v[20:23], v[124:127]
	v_mfma_f32_16x16x32_bf16 v[116:119], v[116:119], v[16:19], v[120:123]
	s_setprio 0
	ds_read_b64_tr_b16 v[148:149], v93
	ds_read_b64_tr_b16 v[150:151], v93 offset:4096
	ds_read_b64_tr_b16 v[132:133], v93 offset:8192
	ds_read_b64_tr_b16 v[134:135], v93 offset:12288
	ds_read_b64_tr_b16 v[128:129], v93 offset:16384
	ds_read_b64_tr_b16 v[130:131], v93 offset:20480
	ds_read_b64_tr_b16 v[124:125], v93 offset:24576
	ds_read_b64_tr_b16 v[126:127], v93 offset:28672
	ds_read_b64_tr_b16 v[120:121], v93 offset:32768
	ds_read_b64_tr_b16 v[122:123], v93 offset:32768
	s_waitcnt lgkmcnt(10)
; __device__ __forceinline__ unsigned cvt_pk_bf16(float lo, float hi) { unsigned r; asm volatile("v_cvt_pk_bf16_f32 %0, %1, %2" : "=v"(r) : "v"(lo), "v"(hi)); return r; }
; #define WG_BAR() do { asm volatile("s_waitcnt lgkmcnt(0)" ::: "memory"); __builtin_amdgcn_s_barrier(); asm volatile("" ::: "memory"); } while (0)
; template <int MODE, class Dec>
; __device__ __forceinline__ void attn_phase(const Frame& F, const bf16* Q, const bf16* K, const bf16* V, int nunits, const Dec dec, const bf16* O3, const float* L2, const float* L3) {
;     ...
;         for (int dt = 0; dt < 8; dt += 2) {
;             tr_issue10((unsigned)(size_t)(vb + (((2 * (dt + 1) + (p4 >> 1)) ^ frl) << 4)), vfb);
;             tr_wait10<10>(vfa);
;             __builtin_amdgcn_s_setprio(1);
;             o[dt] = (f32x4){0.f, 0.f, 0.f, 0.f};
; #pragma unroll
;             for (int pp = 0; pp < 5; ++pp) { const bf16x8 a = __builtin_shufflevector(vfa[2 * pp], vfa[2 * pp + 1], 0, 1, 2, 3, 4, 5, 6, 7);
;                 o[dt] = __builtin_amdgcn_mfma_f32_16x16x32_bf16(a, pf[pp], o[dt], 0, 0, 0); }
;             __builtin_amdgcn_s_setprio(0);
;             if (dt + 2 < 8) { tr_issue10((unsigned)(size_t)(vb + (((2 * (dt + 2) + (p4 >> 1)) ^ frl) << 4)), vfa); tr_wait10<10>(vfb); } else tr_wait10<0>(vfb);
;             __builtin_amdgcn_s_setprio(1);
;             o[dt + 1] = (f32x4){0.f, 0.f, 0.f, 0.f};
; #pragma unroll
;             for (int pp = 0; pp < 5; ++pp) { const bf16x8 a = __builtin_shufflevector(vfb[2 * pp], vfb[2 * pp + 1], 0, 1, 2, 3, 4, 5, 6, 7);
;                 o[dt + 1] = __builtin_amdgcn_mfma_f32_16x16x32_bf16(a, pf[pp], o[dt + 1], 0, 0, 0); }
;             __builtin_amdgcn_s_setprio(0);
;         }
;         WG_BAR();
;         asm volatile("s_waitcnt vmcnt(0)" ::: "memory");
;         const float linv = 1.0f / l, lse = mx + __builtin_amdgcn_logf(l);
;         if (MODE == 0) {
; #pragma unroll
;             for (int dt = 0; dt < 8; ++dt) { v2u wv; wv.x = pg8::cvt_pk_bf16(o[dt][0] * linv, o[dt][1] * linv); wv.y = pg8::cvt_pk_bf16(o[dt][2] * linv, o[dt][3] * linv); *(v2u*)(op + 16 * dt) = wv; }
;             if (g == 0) cur.Lg[qrow * 16 + h] = lse;
	s_setprio 1
	v_mfma_f32_16x16x32_bf16 v[144:147], v[144:147], v[32:35], 0
	v_mfma_f32_16x16x32_bf16 v[140:143], v[140:143], v[28:31], v[144:147]
	v_mfma_f32_16x16x32_bf16 v[136:139], v[136:139], v[24:27], v[140:143]
	v_mfma_f32_16x16x32_bf16 v[112:115], v[112:115], v[20:23], v[136:139]
	v_mfma_f32_16x16x32_bf16 v[108:111], v[108:111], v[16:19], v[112:115]
	s_setprio 0
	ds_read_b64_tr_b16 v[152:153], v94
	ds_read_b64_tr_b16 v[154:155], v94 offset:4096
	ds_read_b64_tr_b16 v[144:145], v94 offset:8192
	ds_read_b64_tr_b16 v[146:147], v94 offset:12288
	ds_read_b64_tr_b16 v[140:141], v94 offset:16384
	ds_read_b64_tr_b16 v[142:143], v94 offset:20480
	ds_read_b64_tr_b16 v[136:137], v94 offset:24576
	ds_read_b64_tr_b16 v[138:139], v94 offset:28672
	ds_read_b64_tr_b16 v[112:113], v94 offset:32768
	ds_read_b64_tr_b16 v[114:115], v94 offset:32768
	s_waitcnt lgkmcnt(10)
	s_setprio 1
	v_mfma_f32_16x16x32_bf16 v[148:151], v[148:151], v[32:35], 0
	v_mfma_f32_16x16x32_bf16 v[132:135], v[132:135], v[28:31], v[148:151]
	v_mfma_f32_16x16x32_bf16 v[128:131], v[128:131], v[24:27], v[132:135]
	v_mfma_f32_16x16x32_bf16 v[124:127], v[124:127], v[20:23], v[128:131]
	v_mfma_f32_16x16x32_bf16 v[120:123], v[120:123], v[16:19], v[124:127]
	s_setprio 0
	ds_read_b64_tr_b16 v[158:159], v95
	ds_read_b64_tr_b16 v[160:161], v95 offset:4096
	ds_read_b64_tr_b16 v[148:149], v95 offset:8192
	ds_read_b64_tr_b16 v[150:151], v95 offset:12288
	ds_read_b64_tr_b16 v[132:133], v95 offset:16384
	ds_read_b64_tr_b16 v[134:135], v95 offset:20480
	ds_read_b64_tr_b16 v[128:129], v95 offset:24576
	ds_read_b64_tr_b16 v[130:131], v95 offset:28672
	ds_read_b64_tr_b16 v[124:125], v95 offset:32768
	ds_read_b64_tr_b16 v[126:127], v95 offset:32768
	s_waitcnt lgkmcnt(10)
	s_setprio 1
	v_mfma_f32_16x16x32_bf16 v[152:155], v[152:155], v[32:35], 0
	v_mfma_f32_16x16x32_bf16 v[144:147], v[144:147], v[28:31], v[152:155]
	v_mfma_f32_16x16x32_bf16 v[140:143], v[140:143], v[24:27], v[144:147]
	v_mfma_f32_16x16x32_bf16 v[136:139], v[136:139], v[20:23], v[140:143]
	v_mfma_f32_16x16x32_bf16 v[112:115], v[112:115], v[16:19], v[136:139]
	s_setprio 0
	s_waitcnt lgkmcnt(0)
	s_setprio 1
	v_mfma_f32_16x16x32_bf16 v[32:35], v[158:161], v[32:35], 0
	v_mfma_f32_16x16x32_bf16 v[28:31], v[148:151], v[28:31], v[32:35]
	v_mfma_f32_16x16x32_bf16 v[24:27], v[132:135], v[24:27], v[28:31]
	v_mfma_f32_16x16x32_bf16 v[20:23], v[128:131], v[20:23], v[24:27]
	v_mfma_f32_16x16x32_bf16 v[16:19], v[124:127], v[16:19], v[20:23]
	s_setprio 0
	s_nop 5
	v_div_scale_f32 v20, s[62:63], v49, v49, 1.0
	v_rcp_f32_e32 v21, v20
	s_waitcnt lgkmcnt(0)
	s_barrier
	v_fma_f32 v22, -v20, v21, 1.0
	v_fmac_f32_e32 v21, v22, v21
	v_div_scale_f32 v22, vcc, 1.0, v49, 1.0
	v_mul_f32_e32 v23, v22, v21
	v_fma_f32 v24, -v20, v23, v22
	v_fmac_f32_e32 v23, v24, v21
	v_fma_f32 v20, -v20, v23, v22
	v_div_fmas_f32 v20, v20, v21, v23
	v_div_fixup_f32 v22, v20, v49, 1.0
	v_mul_f32_e32 v20, v22, v36
	v_mul_f32_e32 v21, v22, v37
	s_waitcnt vmcnt(0)
	v_cvt_pk_bf16_f32 v20, v20, v21
	v_mul_f32_e32 v21, v22, v38
	v_mul_f32_e32 v23, v22, v39
	v_cvt_pk_bf16_f32 v21, v21, v23
	v_bfe_u32 v242, v156, 4, 1
	v_mul_u32_u24_e32 v242, 24, v242
	v_mov_b32_e32 v243, 0
	v_lshl_add_u64 v[240:241], v[46:47], 0, v[242:243]
	v_mov_b32_e32 v236, v20
	v_mov_b32_e32 v237, v21
	v_mul_f32_e32 v20, v22, v40
	v_mul_f32_e32 v21, v22, v41
	v_cvt_pk_bf16_f32 v20, v20, v21
	v_mul_f32_e32 v21, v22, v42
	v_mul_f32_e32 v23, v22, v43
	v_cvt_pk_bf16_f32 v21, v21, v23
	v_mov_b32_e32 v238, v20
	v_mov_b32_e32 v239, v21
	s_nop 1
	v_permlane16_swap_b32 v236, v238
	v_permlane16_swap_b32 v237, v239
	global_store_dwordx4 v[240:241], v[236:239], off
	v_mul_f32_e32 v20, v22, v104
	v_mul_f32_e32 v21, v22, v105
	v_cvt_pk_bf16_f32 v20, v20, v21
	v_mul_f32_e32 v21, v22, v106
	v_mul_f32_e32 v23, v22, v107
	v_cvt_pk_bf16_f32 v21, v21, v23
	v_mov_b32_e32 v236, v20
	v_mov_b32_e32 v237, v21
	v_mul_f32_e32 v20, v22, v116
	v_mul_f32_e32 v21, v22, v117
	v_cvt_pk_bf16_f32 v20, v20, v21
	v_mul_f32_e32 v21, v22, v118
	v_mul_f32_e32 v23, v22, v119
	v_cvt_pk_bf16_f32 v21, v21, v23
	v_mov_b32_e32 v238, v20
	v_mov_b32_e32 v239, v21
	s_nop 1
	v_permlane16_swap_b32 v236, v238
	v_permlane16_swap_b32 v237, v239
	global_store_dwordx4 v[240:241], v[236:239], off offset:64
	v_mul_f32_e32 v20, v22, v108
	v_mul_f32_e32 v21, v22, v109
	v_cvt_pk_bf16_f32 v20, v20, v21
	v_mul_f32_e32 v21, v22, v110
	v_mul_f32_e32 v23, v22, v111
	v_cvt_pk_bf16_f32 v21, v21, v23
	v_mov_b32_e32 v236, v20
	v_mov_b32_e32 v237, v21
	v_mul_f32_e32 v20, v22, v120
	v_mul_f32_e32 v21, v22, v121
	v_cvt_pk_bf16_f32 v20, v20, v21
	v_mul_f32_e32 v21, v22, v122
	v_mul_f32_e32 v23, v22, v123
	v_cvt_pk_bf16_f32 v21, v21, v23
	v_mov_b32_e32 v238, v20
	v_mov_b32_e32 v239, v21
	s_nop 1
	v_permlane16_swap_b32 v236, v238
	v_permlane16_swap_b32 v237, v239
	global_store_dwordx4 v[240:241], v[236:239], off offset:128
	v_mul_f32_e32 v20, v22, v112
	v_mul_f32_e32 v21, v22, v113
	v_cvt_pk_bf16_f32 v20, v20, v21
	v_mul_f32_e32 v21, v22, v114
	v_mul_f32_e32 v16, v22, v16
	v_mul_f32_e32 v17, v22, v17
	v_mul_f32_e32 v23, v22, v115
	v_cvt_pk_bf16_f32 v21, v21, v23
	v_mov_b32_e32 v236, v20
	v_mov_b32_e32 v237, v21
	v_cvt_pk_bf16_f32 v16, v16, v17
	v_mul_f32_e32 v17, v22, v18
	v_mul_f32_e32 v18, v22, v19
	v_cvt_pk_bf16_f32 v17, v17, v18
	v_mov_b32_e32 v238, v16
	v_mov_b32_e32 v239, v17
	s_nop 1
	v_permlane16_swap_b32 v236, v238
	v_permlane16_swap_b32 v237, v239
	global_store_dwordx4 v[240:241], v[236:239], off offset:192
	s_and_saveexec_b64 s[62:63], s[0:1]
	s_cbranch_execz .LBB0_466
	v_log_f32_e32 v18, v49
	v_lshlrev_b64 v[16:17], 6, v[44:45]
	v_lshl_add_u64 v[16:17], s[48:49], 0, v[16:17]
	s_mov_b32 s57, s61
	v_lshl_add_u64 v[16:17], s[56:57], 2, v[16:17]
	v_add_f32_e32 v18, v48, v18
	global_store_dword v[16:17], v18, off

; #define LAS __attribute__((address_space(3)))
; #define WG_BAR() do { asm volatile("s_waitcnt lgkmcnt(0)" ::: "memory"); __builtin_amdgcn_s_barrier(); asm volatile("" ::: "memory"); } while (0)
; template <int MODE, class Dec>
; __device__ __forceinline__ void attn_phase(const Frame& F, const bf16* Q, const bf16* K, const bf16* V, int nunits, const Dec dec, const bf16* O3, const float* L2, const float* L3) {
;     ...
;         const int un = u + F.G; const bool has_next = un < nunits; if (has_next) dec(un, nxt);
;         const int n = cur.n, h = cur.h, d = cur.d;
;         const int qi = 16 * w + ql;
;         const size_t qrow = (size_t)(cur.b * SEQ + (n * 128 + qi) * d + cur.r);
;         WG_BAR();
;         const float sl = exp2f(-0.5f * (float)(h + 1)) * LOG2E * (float)d, cb = -sl * (float)(128 + ql - 4 * g);
;         f32x4 s[9];
;         __builtin_amdgcn_s_setprio(1);
; #pragma unroll
;         for (int tt = 0; tt < 9; ++tt) {
;             s[tt] = (f32x4){fmaf(sl, (float)(16 * tt), cb), fmaf(sl, (float)(16 * tt + 1), cb), fmaf(sl, (float)(16 * tt + 2), cb), fmaf(sl, (float)(16 * tt + 3), cb)};
; #pragma unroll
;             for (int ks = 0; ks < 4; ++ks) { const bf16x8 a = *(const LAS bf16x8*)(kb + ksw[ks] + tt * 4096); s[tt] = __builtin_amdgcn_mfma_f32_16x16x32_bf16(a, qf[ks], s[tt], 0, 0, 0); }
;         }
.LBB0_539:
	s_cmpk_lt_i32 s62, 0x800
	s_cselect_b64 s[50:51], -1, 0
	s_cmpk_gt_i32 s62, 0x7ff
	s_mov_b32 s92, s34
	s_cselect_b64 s[2:3], -1, 0
	s_lshl_b32 s48, s48, 11
	s_lshl_b32 s66, s65, 7
	s_add_i32 s48, s48, s66
	s_add_i32 s66, s92, 1
	v_cvt_f32_u32_e32 v16, s66
	v_add_u32_e32 v52, s48, v130
	s_mov_b32 s48, 0xc2fc0000
	s_bfe_u32 s34, s62, 0x40004
	v_mul_f32_e32 v17, -0.5, v16
	v_cmp_gt_f32_e32 vcc, s48, v17
	s_ashr_i32 s64, s62, 8
	s_and_b64 s[66:67], vcc, exec
	v_cndmask_b32_e32 v17, 0, v144, vcc
	v_fmac_f32_e32 v17, -0.5, v16
	v_exp_f32_e32 v16, v17
	s_waitcnt lgkmcnt(0)
	s_barrier
	s_cselect_b32 s48, 0xffffffc0, 0
	v_ldexp_f32 v16, v16, s48
	v_mul_f32_e32 v54, 0x3fb8aa3b, v16
	v_mul_f32_e64 v56, v131, -v54
	s_setprio 1
	ds_read_b128 v[20:23], v140
	ds_read_b128 v[48:51], v140 offset:28672
	s_mov_b32 s66, 2.0
	s_mov_b32 s67, 0x40400000
	v_fma_f32 v16, 0, v54, v56
	v_fma_f32 v17, v131, -v54, v54
	v_pk_fma_f32 v[18:19], v[54:55], s[66:67], v[56:57] op_sel_hi:[0,1,0]
	s_mov_b32 s66, 0x41900000
	s_mov_b32 s67, 0x41980000
	s_waitcnt lgkmcnt(0)
	v_mfma_f32_16x16x32_bf16 v[16:19], v[20:23], v[0:3], v[16:19]
	ds_read_b128 v[20:23], v141
	v_ashrrev_i32_e32 v53, 31, v52
	s_waitcnt lgkmcnt(0)
	v_mfma_f32_16x16x32_bf16 v[16:19], v[20:23], v[4:7], v[16:19]
	ds_read_b128 v[20:23], v142
	s_waitcnt lgkmcnt(0)
	v_mfma_f32_16x16x32_bf16 v[16:19], v[20:23], v[8:11], v[16:19]
	ds_read_b128 v[20:23], v143
	s_waitcnt lgkmcnt(0)
	v_mfma_f32_16x16x32_bf16 v[44:47], v[20:23], v[12:15], v[16:19]
	ds_read_b128 v[20:23], v140 offset:4096
	s_nop 3
	v_pk_fma_f32 v[18:19], v[54:55], s[66:67], v[56:57] op_sel_hi:[0,1,0]
	s_mov_b32 s66, 0x41800000
	s_mov_b32 s67, 0x41880000
	v_pk_fma_f32 v[16:17], v[54:55], s[66:67], v[56:57] op_sel_hi:[0,1,0]
	s_mov_b32 s66, 0x42080000
	s_mov_b32 s67, 0x420c0000
	s_waitcnt lgkmcnt(0)
	v_mfma_f32_16x16x32_bf16 v[16:19], v[20:23], v[0:3], v[16:19]
	ds_read_b128 v[20:23], v141 offset:4096
	s_waitcnt lgkmcnt(0)
	v_mfma_f32_16x16x32_bf16 v[16:19], v[20:23], v[4:7], v[16:19]
	ds_read_b128 v[20:23], v142 offset:4096
	s_waitcnt lgkmcnt(0)
	v_mfma_f32_16x16x32_bf16 v[16:19], v[20:23], v[8:11], v[16:19]
	ds_read_b128 v[20:23], v143 offset:4096
	s_waitcnt lgkmcnt(0)
	v_mfma_f32_16x16x32_bf16 v[40:43], v[20:23], v[12:15], v[16:19]
	ds_read_b128 v[20:23], v140 offset:8192
	s_nop 3
	v_pk_fma_f32 v[18:19], v[54:55], s[66:67], v[56:57] op_sel_hi:[0,1,0]
	s_mov_b32 s66, 0x42000000
	s_mov_b32 s67, 0x42040000
	v_pk_fma_f32 v[16:17], v[54:55], s[66:67], v[56:57] op_sel_hi:[0,1,0]
	s_mov_b32 s66, 0x42480000
	s_mov_b32 s67, 0x424c0000
	s_waitcnt lgkmcnt(0)
	v_mfma_f32_16x16x32_bf16 v[16:19], v[20:23], v[0:3], v[16:19]
	ds_read_b128 v[20:23], v141 offset:8192
	s_waitcnt lgkmcnt(0)
	v_mfma_f32_16x16x32_bf16 v[16:19], v[20:23], v[4:7], v[16:19]
	ds_read_b128 v[20:23], v142 offset:8192
	s_waitcnt lgkmcnt(0)
	v_mfma_f32_16x16x32_bf16 v[16:19], v[20:23], v[8:11], v[16:19]
	ds_read_b128 v[20:23], v143 offset:8192
	s_waitcnt lgkmcnt(0)
	v_mfma_f32_16x16x32_bf16 v[36:39], v[20:23], v[12:15], v[16:19]
	ds_read_b128 v[20:23], v140 offset:12288
	s_nop 3
	v_pk_fma_f32 v[18:19], v[54:55], s[66:67], v[56:57] op_sel_hi:[0,1,0]
	s_mov_b32 s66, 0x42400000
	s_mov_b32 s67, 0x42440000
	v_pk_fma_f32 v[16:17], v[54:55], s[66:67], v[56:57] op_sel_hi:[0,1,0]
	s_mov_b32 s66, 0x42800000
	s_mov_b32 s67, 0x42820000
	s_waitcnt lgkmcnt(0)
	v_mfma_f32_16x16x32_bf16 v[16:19], v[20:23], v[0:3], v[16:19]
	ds_read_b128 v[20:23], v141 offset:12288
	s_waitcnt lgkmcnt(0)
	v_mfma_f32_16x16x32_bf16 v[16:19], v[20:23], v[4:7], v[16:19]
	ds_read_b128 v[20:23], v142 offset:12288
	s_waitcnt lgkmcnt(0)
	v_mfma_f32_16x16x32_bf16 v[16:19], v[20:23], v[8:11], v[16:19]
	ds_read_b128 v[20:23], v143 offset:12288
	s_waitcnt lgkmcnt(0)
	v_mfma_f32_16x16x32_bf16 v[32:35], v[20:23], v[12:15], v[16:19]
	ds_read_b128 v[20:23], v140 offset:16384
	s_nop 3
	v_pk_fma_f32 v[18:19], v[54:55], s[70:71], v[56:57] op_sel_hi:[0,1,0]
	v_pk_fma_f32 v[16:17], v[54:55], s[66:67], v[56:57] op_sel_hi:[0,1,0]
	s_and_b32 s66, s62, 15
	s_waitcnt lgkmcnt(0)
	v_mfma_f32_16x16x32_bf16 v[16:19], v[20:23], v[0:3], v[16:19]
	ds_read_b128 v[20:23], v141 offset:16384
	s_waitcnt lgkmcnt(0)
	v_mfma_f32_16x16x32_bf16 v[16:19], v[20:23], v[4:7], v[16:19]
	ds_read_b128 v[20:23], v142 offset:16384
	s_waitcnt lgkmcnt(0)
	v_mfma_f32_16x16x32_bf16 v[16:19], v[20:23], v[8:11], v[16:19]
	ds_read_b128 v[20:23], v143 offset:16384
	s_waitcnt lgkmcnt(0)
	v_mfma_f32_16x16x32_bf16 v[28:31], v[20:23], v[12:15], v[16:19]
	ds_read_b128 v[20:23], v140 offset:20480
	s_nop 3
	v_pk_fma_f32 v[18:19], v[54:55], s[72:73], v[56:57] op_sel_hi:[0,1,0]
	v_pk_fma_f32 v[16:17], v[54:55], s[74:75], v[56:57] op_sel_hi:[0,1,0]
	s_waitcnt lgkmcnt(0)
	s_nop 0
	v_mfma_f32_16x16x32_bf16 v[16:19], v[20:23], v[0:3], v[16:19]
	ds_read_b128 v[20:23], v141 offset:20480
	s_waitcnt lgkmcnt(0)
; #define LAS __attribute__((address_space(3)))
; #define WG_BAR() do { asm volatile("s_waitcnt lgkmcnt(0)" ::: "memory"); __builtin_amdgcn_s_barrier(); asm volatile("" ::: "memory"); } while (0)
; template <int MODE, class Dec>
; __device__ __forceinline__ void attn_phase(const Frame& F, const bf16* Q, const bf16* K, const bf16* V, int nunits, const Dec dec, const bf16* O3, const float* L2, const float* L3) {
;     ...
;         for (int tt = 0; tt < 9; ++tt) {
;             s[tt] = (f32x4){fmaf(sl, (float)(16 * tt), cb), fmaf(sl, (float)(16 * tt + 1), cb), fmaf(sl, (float)(16 * tt + 2), cb), fmaf(sl, (float)(16 * tt + 3), cb)};
; #pragma unroll
;             for (int ks = 0; ks < 4; ++ks) { const bf16x8 a = *(const LAS bf16x8*)(kb + ksw[ks] + tt * 4096); s[tt] = __builtin_amdgcn_mfma_f32_16x16x32_bf16(a, qf[ks], s[tt], 0, 0, 0); }
;         }
;         __builtin_amdgcn_s_setprio(0);
;         WG_BAR();
;         v2u a2[8], a3[8]; float l2v = 0.f, l3v = 0.f;
;         bf16* op = cur.Og + qrow * (size_t)cur.ldo + h * 128 + 4 * g;
;         if (MODE == 1) { const bf16* o3p = O3 + qrow * 2048 + h * 128 + 4 * g;
; #pragma unroll
;             for (int dt = 0; dt < 8; ++dt) { a2[dt] = *(const v2u*)(op + 16 * dt); a3[dt] = *(const v2u*)(o3p + 16 * dt); }
;             l2v = L2[qrow * 16 + h]; l3v = L3[qrow * 16 + h]; }
;         if (has_next) { attn_issue<false>(F, K, nxt, 0);
;             q_load4(Q + (size_t)(nxt.b * SEQ + (nxt.n * 128 + qi) * nxt.d + nxt.r) * 2048 + nxt.h * 128 + 8 * g, qn); }
	v_mfma_f32_16x16x32_bf16 v[16:19], v[20:23], v[4:7], v[16:19]
	ds_read_b128 v[20:23], v142 offset:20480
	s_waitcnt lgkmcnt(0)
	v_mfma_f32_16x16x32_bf16 v[16:19], v[20:23], v[8:11], v[16:19]
	ds_read_b128 v[20:23], v143 offset:20480
	s_waitcnt lgkmcnt(0)
	v_mfma_f32_16x16x32_bf16 v[24:27], v[20:23], v[12:15], v[16:19]
	ds_read_b128 v[20:23], v140 offset:24576
	s_nop 3
	v_pk_fma_f32 v[18:19], v[54:55], s[76:77], v[56:57] op_sel_hi:[0,1,0]
	v_pk_fma_f32 v[16:17], v[54:55], s[80:81], v[56:57] op_sel_hi:[0,1,0]
	s_waitcnt lgkmcnt(0)
	s_nop 0
	v_mfma_f32_16x16x32_bf16 v[16:19], v[20:23], v[0:3], v[16:19]
	ds_read_b128 v[20:23], v141 offset:24576
	s_waitcnt lgkmcnt(0)
	v_mfma_f32_16x16x32_bf16 v[16:19], v[20:23], v[4:7], v[16:19]
	ds_read_b128 v[20:23], v142 offset:24576
	s_waitcnt lgkmcnt(0)
	v_mfma_f32_16x16x32_bf16 v[16:19], v[20:23], v[8:11], v[16:19]
	ds_read_b128 v[20:23], v143 offset:24576
	s_waitcnt lgkmcnt(0)
	v_mfma_f32_16x16x32_bf16 v[20:23], v[20:23], v[12:15], v[16:19]
	s_nop 4
	v_fma_f32 v18, v54, s96, v56
	v_fma_f32 v19, v54, s97, v56
	v_pk_fma_f32 v[16:17], v[54:55], s[94:95], v[56:57] op_sel_hi:[0,1,0]
	s_nop 1
	v_mfma_f32_16x16x32_bf16 v[16:19], v[48:51], v[0:3], v[16:19]
	ds_read_b128 v[48:51], v141 offset:28672
	s_waitcnt lgkmcnt(0)
	v_mfma_f32_16x16x32_bf16 v[16:19], v[48:51], v[4:7], v[16:19]
	ds_read_b128 v[48:51], v142 offset:28672
	s_waitcnt lgkmcnt(0)
	v_mfma_f32_16x16x32_bf16 v[16:19], v[48:51], v[8:11], v[16:19]
	ds_read_b128 v[48:51], v143 offset:28672
	s_waitcnt lgkmcnt(0)
	v_mfma_f32_16x16x32_bf16 v[16:19], v[48:51], v[12:15], v[16:19]
	v_fma_f32 v50, v54, s78, v56
	v_fma_f32 v51, v54, s79, v56
	v_pk_fma_f32 v[48:49], v[54:55], s[82:83], v[56:57] op_sel_hi:[0,1,0]
	ds_read_b128 v[54:57], v140 offset:32768
	s_waitcnt lgkmcnt(0)
	v_mfma_f32_16x16x32_bf16 v[48:51], v[54:57], v[0:3], v[48:51]
	ds_read_b128 v[54:57], v141 offset:32768
	s_waitcnt lgkmcnt(0)
	v_mfma_f32_16x16x32_bf16 v[48:51], v[54:57], v[4:7], v[48:51]
	ds_read_b128 v[54:57], v142 offset:32768
	s_waitcnt lgkmcnt(0)
	v_mfma_f32_16x16x32_bf16 v[48:51], v[54:57], v[8:11], v[48:51]
	ds_read_b128 v[54:57], v143 offset:32768
	s_waitcnt lgkmcnt(0)
	v_mfma_f32_16x16x32_bf16 v[48:51], v[54:57], v[12:15], v[48:51]
	s_setprio 0
	v_lshlrev_b64 v[54:55], 13, v[52:53]
	v_lshl_add_u64 v[54:55], s[86:87], 0, v[54:55]
	s_lshl_b32 s48, s92, 8
	v_lshl_add_u64 v[54:55], v[54:55], 0, s[48:49]
	v_lshl_add_u64 v[92:93], v[54:55], 0, v[74:75]
	v_lshlrev_b64 v[54:55], 12, v[52:53]
	v_lshl_add_u64 v[54:55], s[42:43], 0, v[54:55]
	s_waitcnt lgkmcnt(0)
	s_barrier
	v_lshl_add_u64 v[54:55], v[54:55], 0, s[48:49]
	v_lshl_add_u64 v[54:55], v[54:55], 0, v[74:75]
	v_bfe_u32 v242, v156, 4, 1
	v_mul_u32_u24_e32 v242, 24, v242
	v_mov_b32_e32 v243, 0
	v_lshl_add_u64 v[240:241], v[92:93], 0, v[242:243]
	v_lshl_add_u64 v[244:245], v[54:55], 0, v[242:243]
	global_load_dwordx4 v[94:97], v[240:241], off
	global_load_dwordx4 v[98:101], v[244:245], off
	global_load_dwordx4 v[102:105], v[240:241], off offset:64
	global_load_dwordx4 v[106:109], v[244:245], off offset:64
	global_load_dwordx4 v[110:113], v[240:241], off offset:128
	global_load_dwordx4 v[114:117], v[244:245], off offset:128
	global_load_dwordx4 v[118:121], v[240:241], off offset:192
	global_load_dwordx4 v[122:125], v[244:245], off offset:192
	s_mov_b32 s93, s49
	v_lshlrev_b64 v[52:53], 6, v[52:53]
	s_lshl_b64 s[68:69], s[92:93], 2
	v_or_b32_e32 v53, s69, v53
	v_or_b32_e32 v52, s68, v52
	v_lshl_add_u64 v[54:55], s[44:45], 0, v[52:53]
	v_lshl_add_u64 v[52:53], s[46:47], 0, v[52:53]
	global_load_dword v147, v[54:55], off
	global_load_dword v148, v[52:53], off
	s_and_b64 vcc, exec, s[2:3]
	s_cbranch_vccnz .LBB0_544
	s_lshl_b32 s67, s64, 11
	s_cmp_lg_u32 s66, 0
	s_cbranch_scc0 .LBB0_555
	s_lshl_b32 s68, s66, 7
	s_add_i32 s48, s68, s67
	s_add_i32 s69, s48, 0xffffff80
	v_add_u32_e32 v0, s69, v127
	v_ashrrev_i32_e32 v1, 31, v0
	v_lshlrev_b64 v[0:1], 11, v[0:1]
	s_lshl_b32 s48, s34, 7
	v_or_b32_e32 v0, v0, v82
	v_or_b32_e32 v0, s48, v0
	v_lshl_add_u64 v[0:1], v[0:1], 1, s[36:37]
	s_add_i32 m0, s35, 0
	s_nop 0
	global_load_lds_dwordx4 v[0:1], off
	v_add_u32_e32 v0, s69, v126
	v_ashrrev_i32_e32 v1, 31, v0
	v_lshlrev_b64 v[0:1], 11, v[0:1]
	v_or_b32_e32 v0, v0, v84
	v_or_b32_e32 v0, s48, v0
	v_lshl_add_u64 v[0:1], v[0:1], 1, s[36:37]
	s_add_i32 m0, s54, 0
	s_nop 0
	global_load_lds_dwordx4 v[0:1], off
	v_add_u32_e32 v0, s69, v128
	v_ashrrev_i32_e32 v1, 31, v0
	v_lshlrev_b64 v[0:1], 11, v[0:1]
	v_or_b32_e32 v0, v0, v86
	v_or_b32_e32 v0, s48, v0
	v_lshl_add_u64 v[0:1], v[0:1], 1, s[36:37]
	s_add_i32 m0, s55, 0
	s_nop 0
	global_load_lds_dwordx4 v[0:1], off
	v_add_u32_e32 v0, s69, v129
	v_ashrrev_i32_e32 v1, 31, v0
	v_lshlrev_b64 v[0:1], 11, v[0:1]
	v_or_b32_e32 v0, v0, v88
	v_or_b32_e32 v0, s48, v0
	v_lshl_add_u64 v[0:1], v[0:1], 1, s[36:37]
	s_add_i32 m0, s56, 0
	s_nop 0
	global_load_lds_dwordx4 v[0:1], off
	s_cbranch_execnz .LBB0_543

; #define WG_BAR() do { asm volatile("s_waitcnt lgkmcnt(0)" ::: "memory"); __builtin_amdgcn_s_barrier(); asm volatile("" ::: "memory"); } while (0)
; template <int MODE, class Dec>
; __device__ __forceinline__ void attn_phase(const Frame& F, const bf16* Q, const bf16* K, const bf16* V, int nunits, const Dec dec, const bf16* O3, const float* L2, const float* L3) {
;     ...
;         WG_BAR();
;         f32x4 o[8];
;         s16x4 vfa[10], vfb[10];
;         tr_issue10((unsigned)(size_t)(vb + (((p4 >> 1)) ^ frl) * 16), vfa);
; #pragma unroll
;         for (int dt = 0; dt < 8; dt += 2) {
;             tr_issue10((unsigned)(size_t)(vb + (((2 * (dt + 1) + (p4 >> 1)) ^ frl) << 4)), vfb);
;             tr_wait10<10>(vfa);
;             __builtin_amdgcn_s_setprio(1);
;             o[dt] = (f32x4){0.f, 0.f, 0.f, 0.f};
; #pragma unroll
;             for (int pp = 0; pp < 5; ++pp) { const bf16x8 a = __builtin_shufflevector(vfa[2 * pp], vfa[2 * pp + 1], 0, 1, 2, 3, 4, 5, 6, 7);
;                 o[dt] = __builtin_amdgcn_mfma_f32_16x16x32_bf16(a, pf[pp], o[dt], 0, 0, 0); }
;             __builtin_amdgcn_s_setprio(0);
;             if (dt + 2 < 8) { tr_issue10((unsigned)(size_t)(vb + (((2 * (dt + 2) + (p4 >> 1)) ^ frl) << 4)), vfa); tr_wait10<10>(vfb); } else tr_wait10<0>(vfb);
;             __builtin_amdgcn_s_setprio(1);
;             o[dt + 1] = (f32x4){0.f, 0.f, 0.f, 0.f};
; #pragma unroll
;             for (int pp = 0; pp < 5; ++pp) { const bf16x8 a = __builtin_shufflevector(vfb[2 * pp], vfb[2 * pp + 1], 0, 1, 2, 3, 4, 5, 6, 7);
;                 o[dt + 1] = __builtin_amdgcn_mfma_f32_16x16x32_bf16(a, pf[pp], o[dt + 1], 0, 0, 0); }
;             __builtin_amdgcn_s_setprio(0);
.LBB0_552:
	s_waitcnt lgkmcnt(0)
	s_barrier
	s_waitcnt lgkmcnt(0)
	v_add_f32_e32 v149, v16, v17
	ds_read_b64_tr_b16 v[32:33], v132
	ds_read_b64_tr_b16 v[34:35], v132 offset:4096
	ds_read_b64_tr_b16 v[28:29], v132 offset:8192
	ds_read_b64_tr_b16 v[30:31], v132 offset:12288
	ds_read_b64_tr_b16 v[24:25], v132 offset:16384
	ds_read_b64_tr_b16 v[26:27], v132 offset:20480
	ds_read_b64_tr_b16 v[20:21], v132 offset:24576
	ds_read_b64_tr_b16 v[22:23], v132 offset:28672
	ds_read_b64_tr_b16 v[16:17], v132 offset:32768
	ds_read_b64_tr_b16 v[18:19], v132 offset:32768
	ds_read_b64_tr_b16 v[162:163], v133
	ds_read_b64_tr_b16 v[164:165], v133 offset:4096
	ds_read_b64_tr_b16 v[158:159], v133 offset:8192
	ds_read_b64_tr_b16 v[160:161], v133 offset:12288
	ds_read_b64_tr_b16 v[150:151], v133 offset:16384
	ds_read_b64_tr_b16 v[152:153], v133 offset:20480
	ds_read_b64_tr_b16 v[40:41], v133 offset:24576
	ds_read_b64_tr_b16 v[42:43], v133 offset:28672
	ds_read_b64_tr_b16 v[36:37], v133 offset:32768
	ds_read_b64_tr_b16 v[38:39], v133 offset:32768
	s_nop 0
	s_waitcnt lgkmcnt(10)
	s_setprio 1
	v_mfma_f32_16x16x32_bf16 v[32:35], v[32:35], v[60:63], 0
	v_mfma_f32_16x16x32_bf16 v[28:31], v[28:31], v[56:59], v[32:35]
	v_mfma_f32_16x16x32_bf16 v[24:27], v[24:27], v[52:55], v[28:31]
	v_mfma_f32_16x16x32_bf16 v[20:23], v[20:23], v[48:51], v[24:27]
	v_mfma_f32_16x16x32_bf16 v[16:19], v[16:19], v[44:47], v[20:23]
	s_setprio 0
	ds_read_b64_tr_b16 v[170:171], v134
	ds_read_b64_tr_b16 v[172:173], v134 offset:4096
	ds_read_b64_tr_b16 v[166:167], v134 offset:8192
	ds_read_b64_tr_b16 v[168:169], v134 offset:12288
	ds_read_b64_tr_b16 v[32:33], v134 offset:16384
	ds_read_b64_tr_b16 v[34:35], v134 offset:20480
	ds_read_b64_tr_b16 v[28:29], v134 offset:24576
	ds_read_b64_tr_b16 v[30:31], v134 offset:28672
	ds_read_b64_tr_b16 v[24:25], v134 offset:32768
	ds_read_b64_tr_b16 v[26:27], v134 offset:32768
	s_waitcnt lgkmcnt(10)
	s_setprio 1
	v_mfma_f32_16x16x32_bf16 v[20:23], v[162:165], v[60:63], 0
	v_mfma_f32_16x16x32_bf16 v[20:23], v[158:161], v[56:59], v[20:23]
	v_mfma_f32_16x16x32_bf16 v[20:23], v[150:153], v[52:55], v[20:23]
	v_mfma_f32_16x16x32_bf16 v[20:23], v[40:43], v[48:51], v[20:23]
	v_mfma_f32_16x16x32_bf16 v[20:23], v[36:39], v[44:47], v[20:23]
	s_setprio 0
	ds_read_b64_tr_b16 v[162:163], v135
	ds_read_b64_tr_b16 v[164:165], v135 offset:4096
	ds_read_b64_tr_b16 v[158:159], v135 offset:8192
	ds_read_b64_tr_b16 v[160:161], v135 offset:12288
	ds_read_b64_tr_b16 v[150:151], v135 offset:16384
	ds_read_b64_tr_b16 v[152:153], v135 offset:20480
	ds_read_b64_tr_b16 v[40:41], v135 offset:24576
	ds_read_b64_tr_b16 v[42:43], v135 offset:28672
	ds_read_b64_tr_b16 v[36:37], v135 offset:32768
	ds_read_b64_tr_b16 v[38:39], v135 offset:32768
	s_waitcnt lgkmcnt(10)
	s_setprio 1
	v_mfma_f32_16x16x32_bf16 v[170:173], v[170:173], v[60:63], 0
	v_mfma_f32_16x16x32_bf16 v[166:169], v[166:169], v[56:59], v[170:173]
	v_mfma_f32_16x16x32_bf16 v[32:35], v[32:35], v[52:55], v[166:169]
	v_mfma_f32_16x16x32_bf16 v[28:31], v[28:31], v[48:51], v[32:35]
	v_mfma_f32_16x16x32_bf16 v[24:27], v[24:27], v[44:47], v[28:31]
	s_setprio 0
	ds_read_b64_tr_b16 v[178:179], v136
	ds_read_b64_tr_b16 v[180:181], v136 offset:4096
	ds_read_b64_tr_b16 v[174:175], v136 offset:8192
	ds_read_b64_tr_b16 v[176:177], v136 offset:12288
	ds_read_b64_tr_b16 v[170:171], v136 offset:16384
	ds_read_b64_tr_b16 v[172:173], v136 offset:20480
	ds_read_b64_tr_b16 v[166:167], v136 offset:24576
	ds_read_b64_tr_b16 v[168:169], v136 offset:28672
	ds_read_b64_tr_b16 v[32:33], v136 offset:32768
	ds_read_b64_tr_b16 v[34:35], v136 offset:32768
	s_waitcnt lgkmcnt(10)
	s_setprio 1
	v_mfma_f32_16x16x32_bf16 v[28:31], v[162:165], v[60:63], 0
	v_mfma_f32_16x16x32_bf16 v[28:31], v[158:161], v[56:59], v[28:31]
	v_mfma_f32_16x16x32_bf16 v[28:31], v[150:153], v[52:55], v[28:31]
	v_mfma_f32_16x16x32_bf16 v[28:31], v[40:43], v[48:51], v[28:31]
	v_mfma_f32_16x16x32_bf16 v[28:31], v[36:39], v[44:47], v[28:31]
	s_setprio 0
	ds_read_b64_tr_b16 v[162:163], v137
	ds_read_b64_tr_b16 v[164:165], v137 offset:4096
	ds_read_b64_tr_b16 v[158:159], v137 offset:8192
	ds_read_b64_tr_b16 v[160:161], v137 offset:12288
	ds_read_b64_tr_b16 v[150:151], v137 offset:16384
	ds_read_b64_tr_b16 v[152:153], v137 offset:20480
	ds_read_b64_tr_b16 v[40:41], v137 offset:24576
	ds_read_b64_tr_b16 v[42:43], v137 offset:28672
	ds_read_b64_tr_b16 v[36:37], v137 offset:32768
	ds_read_b64_tr_b16 v[38:39], v137 offset:32768
	s_waitcnt lgkmcnt(10)
	s_setprio 1
	v_mfma_f32_16x16x32_bf16 v[178:181], v[178:181], v[60:63], 0
	v_mfma_f32_16x16x32_bf16 v[174:177], v[174:177], v[56:59], v[178:181]
	v_mfma_f32_16x16x32_bf16 v[170:173], v[170:173], v[52:55], v[174:177]
	v_mfma_f32_16x16x32_bf16 v[166:169], v[166:169], v[48:51], v[170:173]
	v_mfma_f32_16x16x32_bf16 v[32:35], v[32:35], v[44:47], v[166:169]
	s_setprio 0
	ds_read_b64_tr_b16 v[182:183], v138
	ds_read_b64_tr_b16 v[184:185], v138 offset:4096
	ds_read_b64_tr_b16 v[178:179], v138 offset:8192
	ds_read_b64_tr_b16 v[180:181], v138 offset:12288
	ds_read_b64_tr_b16 v[174:175], v138 offset:16384
	ds_read_b64_tr_b16 v[176:177], v138 offset:20480
	ds_read_b64_tr_b16 v[170:171], v138 offset:24576
	ds_read_b64_tr_b16 v[172:173], v138 offset:28672
	ds_read_b64_tr_b16 v[166:167], v138 offset:32768
	ds_read_b64_tr_b16 v[168:169], v138 offset:32768
	s_waitcnt lgkmcnt(10)
; __device__ __forceinline__ unsigned cvt_pk_bf16(float lo, float hi) { unsigned r; asm volatile("v_cvt_pk_bf16_f32 %0, %1, %2" : "=v"(r) : "v"(lo), "v"(hi)); return r; }
; __device__ __forceinline__ float bf_lo(unsigned w) { return __uint_as_float(w << 16); }
; __device__ __forceinline__ float bf_hi(unsigned w) { return __uint_as_float(w & 0xffff0000u); }
; #define WG_BAR() do { asm volatile("s_waitcnt lgkmcnt(0)" ::: "memory"); __builtin_amdgcn_s_barrier(); asm volatile("" ::: "memory"); } while (0)
; template <int MODE, class Dec>
; __device__ __forceinline__ void attn_phase(const Frame& F, const bf16* Q, const bf16* K, const bf16* V, int nunits, const Dec dec, const bf16* O3, const float* L2, const float* L3) {
;     ...
;         WG_BAR();
;         asm volatile("s_waitcnt vmcnt(0)" ::: "memory");
;         const float linv = 1.0f / l, lse = mx + __builtin_amdgcn_logf(l);
;         if (MODE == 0) {
; #pragma unroll
;             for (int dt = 0; dt < 8; ++dt) { v2u wv; wv.x = pg8::cvt_pk_bf16(o[dt][0] * linv, o[dt][1] * linv); wv.y = pg8::cvt_pk_bf16(o[dt][2] * linv, o[dt][3] * linv); *(v2u*)(op + 16 * dt) = wv; }
;             if (g == 0) cur.Lg[qrow * 16 + h] = lse;
;         } else {
;             const float mm = fmaxf(lse, fmaxf(l2v, l3v));
;             float w1 = __builtin_amdgcn_exp2f(lse - mm), w2 = __builtin_amdgcn_exp2f(l2v - mm), w3 = __builtin_amdgcn_exp2f(l3v - mm); const float wi = 1.0f / (w1 + w2 + w3);
;             w1 *= wi * linv; w2 *= wi; w3 *= wi;
; #pragma unroll
;             for (int dt = 0; dt < 8; ++dt) {
;                 const float y0 = w1 * o[dt][0] + w2 * pg8::bf_lo(a2[dt].x) + w3 * pg8::bf_lo(a3[dt].x), y1 = w1 * o[dt][1] + w2 * pg8::bf_hi(a2[dt].x) + w3 * pg8::bf_hi(a3[dt].x);
;                 const float y2 = w1 * o[dt][2] + w2 * pg8::bf_lo(a2[dt].y) + w3 * pg8::bf_lo(a3[dt].y), y3 = w1 * o[dt][3] + w2 * pg8::bf_hi(a2[dt].y) + w3 * pg8::bf_hi(a3[dt].y);
;                 v2u wv; wv.x = pg8::cvt_pk_bf16(y0, y1); wv.y = pg8::cvt_pk_bf16(y2, y3); *(v2u*)(op + 16 * dt) = wv; }
	s_setprio 1
	v_mfma_f32_16x16x32_bf16 v[162:165], v[162:165], v[60:63], 0
	v_mfma_f32_16x16x32_bf16 v[158:161], v[158:161], v[56:59], v[162:165]
	v_mfma_f32_16x16x32_bf16 v[150:153], v[150:153], v[52:55], v[158:161]
	v_mfma_f32_16x16x32_bf16 v[40:43], v[40:43], v[48:51], v[150:153]
	v_mfma_f32_16x16x32_bf16 v[36:39], v[36:39], v[44:47], v[40:43]
	s_setprio 0
	ds_read_b64_tr_b16 v[190:191], v139
	ds_read_b64_tr_b16 v[192:193], v139 offset:4096
	ds_read_b64_tr_b16 v[186:187], v139 offset:8192
	ds_read_b64_tr_b16 v[188:189], v139 offset:12288
	ds_read_b64_tr_b16 v[162:163], v139 offset:16384
	ds_read_b64_tr_b16 v[164:165], v139 offset:20480
	ds_read_b64_tr_b16 v[158:159], v139 offset:24576
	ds_read_b64_tr_b16 v[160:161], v139 offset:28672
	ds_read_b64_tr_b16 v[150:151], v139 offset:32768
	ds_read_b64_tr_b16 v[152:153], v139 offset:32768
	s_waitcnt lgkmcnt(10)
	s_setprio 1
	v_mfma_f32_16x16x32_bf16 v[40:43], v[182:185], v[60:63], 0
	v_mfma_f32_16x16x32_bf16 v[40:43], v[178:181], v[56:59], v[40:43]
	v_mfma_f32_16x16x32_bf16 v[40:43], v[174:177], v[52:55], v[40:43]
	v_mfma_f32_16x16x32_bf16 v[40:43], v[170:173], v[48:51], v[40:43]
	v_mfma_f32_16x16x32_bf16 v[40:43], v[166:169], v[44:47], v[40:43]
	s_setprio 0
	s_waitcnt lgkmcnt(0)
	s_setprio 1
	v_mfma_f32_16x16x32_bf16 v[60:63], v[190:193], v[60:63], 0
	v_mfma_f32_16x16x32_bf16 v[56:59], v[186:189], v[56:59], v[60:63]
	v_mfma_f32_16x16x32_bf16 v[52:55], v[162:165], v[52:55], v[56:59]
	v_mfma_f32_16x16x32_bf16 v[48:51], v[158:161], v[48:51], v[52:55]
	v_mfma_f32_16x16x32_bf16 v[44:47], v[150:153], v[44:47], v[48:51]
	s_setprio 0
	s_nop 5
	v_div_scale_f32 v48, s[2:3], v149, v149, 1.0
	v_rcp_f32_e32 v49, v48
	s_waitcnt lgkmcnt(0)
	s_barrier
	v_fma_f32 v50, -v48, v49, 1.0
	v_fmac_f32_e32 v49, v50, v49
	v_div_scale_f32 v50, vcc, 1.0, v149, 1.0
	v_mul_f32_e32 v51, v50, v49
	v_fma_f32 v52, -v48, v51, v50
	v_fmac_f32_e32 v51, v52, v49
	v_fma_f32 v48, -v48, v51, v50
	v_div_fmas_f32 v48, v48, v49, v51
	v_div_fixup_f32 v51, v48, v149, 1.0
	v_log_f32_e32 v48, v149
	s_waitcnt vmcnt(0)
	s_nop 0
	v_add_f32_e32 v48, v91, v48
	s_waitcnt vmcnt(0)
	v_permlane16_swap_b32 v94, v96
	v_permlane16_swap_b32 v95, v97
	v_permlane16_swap_b32 v102, v104
	v_permlane16_swap_b32 v103, v105
	v_permlane16_swap_b32 v110, v112
	v_permlane16_swap_b32 v111, v113
	v_permlane16_swap_b32 v118, v120
	v_permlane16_swap_b32 v119, v121
	v_permlane16_swap_b32 v98, v100
	v_permlane16_swap_b32 v99, v101
	v_permlane16_swap_b32 v106, v108
	v_permlane16_swap_b32 v107, v109
	v_permlane16_swap_b32 v114, v116
	v_permlane16_swap_b32 v115, v117
	v_permlane16_swap_b32 v122, v124
	v_permlane16_swap_b32 v123, v125
	v_max3_f32 v50, v48, v147, v148
	v_sub_f32_e32 v48, v48, v50
	v_exp_f32_e32 v52, v48
	v_sub_f32_e32 v48, v147, v50
	v_exp_f32_e32 v49, v48
	v_sub_f32_e32 v48, v148, v50
	v_exp_f32_e32 v48, v48
	v_add_f32_e32 v50, v52, v49
	v_add_f32_e32 v50, v48, v50
	v_div_scale_f32 v53, s[2:3], v50, v50, 1.0
	v_rcp_f32_e32 v54, v53
	s_mov_b64 s[2:3], -1
	v_fma_f32 v55, -v53, v54, 1.0
	v_fmac_f32_e32 v54, v55, v54
	v_div_scale_f32 v55, vcc, 1.0, v50, 1.0
	v_mul_f32_e32 v56, v55, v54
	v_fma_f32 v57, -v53, v56, v55
	v_fmac_f32_e32 v56, v57, v54
	v_fma_f32 v53, -v53, v56, v55
	v_div_fmas_f32 v53, v53, v54, v56
	v_div_fixup_f32 v50, v53, v50, 1.0
	v_mul_f32_e32 v51, v51, v50
	v_mul_f32_e32 v52, v52, v51
	v_pk_mul_f32 v[48:49], v[48:49], v[50:51] op_sel_hi:[1,0]
	v_lshlrev_b32_e32 v51, 16, v94
	v_lshlrev_b32_e32 v50, 16, v98
	v_pk_mul_f32 v[50:51], v[48:49], v[50:51]
	s_andn2_b64 vcc, exec, s[50:51]
	v_fma_f32 v16, v52, v16, v51
	v_add_f32_e32 v53, v50, v16
	v_and_b32_e32 v51, 0xffff0000, v94
	v_and_b32_e32 v50, 0xffff0000, v98
	v_pk_mul_f32 v[50:51], v[48:49], v[50:51]
	s_nop 0
	v_fma_f32 v16, v52, v17, v51
	v_add_f32_e32 v50, v50, v16
	v_lshlrev_b32_e32 v17, 16, v95
	v_lshlrev_b32_e32 v16, 16, v99
	v_pk_mul_f32 v[16:17], v[48:49], v[16:17]
	s_nop 0
	v_fma_f32 v17, v52, v18, v17
	v_add_f32_e32 v18, v16, v17
	v_and_b32_e32 v17, 0xffff0000, v95
	v_and_b32_e32 v16, 0xffff0000, v99
	v_pk_mul_f32 v[16:17], v[48:49], v[16:17]
	s_nop 0
	v_fma_f32 v17, v52, v19, v17
	v_add_f32_e32 v17, v16, v17
	v_cvt_pk_bf16_f32 v16, v53, v50
	v_cvt_pk_bf16_f32 v17, v18, v17
	v_mov_b32_e32 v236, v16
	v_mov_b32_e32 v237, v17
	v_lshlrev_b32_e32 v17, 16, v96
	v_lshlrev_b32_e32 v16, 16, v100
	v_pk_mul_f32 v[16:17], v[48:49], v[16:17]
	s_nop 0
	v_fma_f32 v17, v52, v20, v17
	v_add_f32_e32 v18, v16, v17
	v_and_b32_e32 v17, 0xffff0000, v96
	v_and_b32_e32 v16, 0xffff0000, v100
	v_pk_mul_f32 v[16:17], v[48:49], v[16:17]
	s_nop 0
	v_fma_f32 v17, v52, v21, v17
	v_add_f32_e32 v19, v16, v17
	v_lshlrev_b32_e32 v17, 16, v97
	v_lshlrev_b32_e32 v16, 16, v101
	v_pk_mul_f32 v[16:17], v[48:49], v[16:17]
	s_nop 0
	v_fma_f32 v17, v52, v22, v17
	v_add_f32_e32 v20, v16, v17
	v_and_b32_e32 v17, 0xffff0000, v97
	v_and_b32_e32 v16, 0xffff0000, v101
	v_pk_mul_f32 v[16:17], v[48:49], v[16:17]
	s_nop 0
	v_fma_f32 v17, v52, v23, v17
	v_add_f32_e32 v17, v16, v17
	v_cvt_pk_bf16_f32 v16, v18, v19
	v_cvt_pk_bf16_f32 v17, v20, v17
	v_mov_b32_e32 v238, v16
	v_mov_b32_e32 v239, v17
	s_nop 1
	v_permlane16_swap_b32 v236, v238
	v_permlane16_swap_b32 v237, v239
	global_store_dwordx4 v[240:241], v[236:239], off
	v_lshlrev_b32_e32 v17, 16, v102
	v_lshlrev_b32_e32 v16, 16, v106
	v_pk_mul_f32 v[16:17], v[48:49], v[16:17]
	s_nop 0
	v_fma_f32 v17, v52, v24, v17
	v_add_f32_e32 v18, v16, v17
	v_and_b32_e32 v17, 0xffff0000, v102
	v_and_b32_e32 v16, 0xffff0000, v106
	v_pk_mul_f32 v[16:17], v[48:49], v[16:17]
	s_nop 0
	v_fma_f32 v17, v52, v25, v17
	v_add_f32_e32 v19, v16, v17
	v_lshlrev_b32_e32 v17, 16, v103
	v_lshlrev_b32_e32 v16, 16, v107
; __device__ __forceinline__ unsigned cvt_pk_bf16(float lo, float hi) { unsigned r; asm volatile("v_cvt_pk_bf16_f32 %0, %1, %2" : "=v"(r) : "v"(lo), "v"(hi)); return r; }
; __device__ __forceinline__ float bf_lo(unsigned w) { return __uint_as_float(w << 16); }
; __device__ __forceinline__ float bf_hi(unsigned w) { return __uint_as_float(w & 0xffff0000u); }
; template <int MODE, class Dec>
; __device__ __forceinline__ void attn_phase(const Frame& F, const bf16* Q, const bf16* K, const bf16* V, int nunits, const Dec dec, const bf16* O3, const float* L2, const float* L3) {
;     ...
;             for (int dt = 0; dt < 8; ++dt) {
;                 const float y0 = w1 * o[dt][0] + w2 * pg8::bf_lo(a2[dt].x) + w3 * pg8::bf_lo(a3[dt].x), y1 = w1 * o[dt][1] + w2 * pg8::bf_hi(a2[dt].x) + w3 * pg8::bf_hi(a3[dt].x);
;                 const float y2 = w1 * o[dt][2] + w2 * pg8::bf_lo(a2[dt].y) + w3 * pg8::bf_lo(a3[dt].y), y3 = w1 * o[dt][3] + w2 * pg8::bf_hi(a2[dt].y) + w3 * pg8::bf_hi(a3[dt].y);
;                 v2u wv; wv.x = pg8::cvt_pk_bf16(y0, y1); wv.y = pg8::cvt_pk_bf16(y2, y3); *(v2u*)(op + 16 * dt) = wv; }
;         }
;         if (!has_next) break;
;         attn_issue<true>(F, V, nxt, 65536);
	v_pk_mul_f32 v[16:17], v[48:49], v[16:17]
	s_nop 0
	v_fma_f32 v17, v52, v26, v17
	v_add_f32_e32 v20, v16, v17
	v_and_b32_e32 v17, 0xffff0000, v103
	v_and_b32_e32 v16, 0xffff0000, v107
	v_pk_mul_f32 v[16:17], v[48:49], v[16:17]
	s_nop 0
	v_fma_f32 v17, v52, v27, v17
	v_add_f32_e32 v17, v16, v17
	v_cvt_pk_bf16_f32 v16, v18, v19
	v_cvt_pk_bf16_f32 v17, v20, v17
	v_mov_b32_e32 v236, v16
	v_mov_b32_e32 v237, v17
	v_lshlrev_b32_e32 v17, 16, v104
	v_lshlrev_b32_e32 v16, 16, v108
	v_pk_mul_f32 v[16:17], v[48:49], v[16:17]
	s_nop 0
	v_fma_f32 v17, v52, v28, v17
	v_add_f32_e32 v18, v16, v17
	v_and_b32_e32 v17, 0xffff0000, v104
	v_and_b32_e32 v16, 0xffff0000, v108
	v_pk_mul_f32 v[16:17], v[48:49], v[16:17]
	s_nop 0
	v_fma_f32 v17, v52, v29, v17
	v_add_f32_e32 v19, v16, v17
	v_lshlrev_b32_e32 v17, 16, v105
	v_lshlrev_b32_e32 v16, 16, v109
	v_pk_mul_f32 v[16:17], v[48:49], v[16:17]
	s_nop 0
	v_fma_f32 v17, v52, v30, v17
	v_add_f32_e32 v20, v16, v17
	v_and_b32_e32 v17, 0xffff0000, v105
	v_and_b32_e32 v16, 0xffff0000, v109
	v_pk_mul_f32 v[16:17], v[48:49], v[16:17]
	s_nop 0
	v_fma_f32 v17, v52, v31, v17
	v_add_f32_e32 v17, v16, v17
	v_cvt_pk_bf16_f32 v16, v18, v19
	v_cvt_pk_bf16_f32 v17, v20, v17
	v_mov_b32_e32 v238, v16
	v_mov_b32_e32 v239, v17
	s_nop 1
	v_permlane16_swap_b32 v236, v238
	v_permlane16_swap_b32 v237, v239
	global_store_dwordx4 v[240:241], v[236:239], off offset:64
	v_lshlrev_b32_e32 v17, 16, v110
	v_lshlrev_b32_e32 v16, 16, v114
	v_pk_mul_f32 v[16:17], v[48:49], v[16:17]
	s_nop 0
	v_fma_f32 v17, v52, v32, v17
	v_add_f32_e32 v18, v16, v17
	v_and_b32_e32 v17, 0xffff0000, v110
	v_and_b32_e32 v16, 0xffff0000, v114
	v_pk_mul_f32 v[16:17], v[48:49], v[16:17]
	s_nop 0
	v_fma_f32 v17, v52, v33, v17
	v_add_f32_e32 v19, v16, v17
	v_lshlrev_b32_e32 v17, 16, v111
	v_lshlrev_b32_e32 v16, 16, v115
	v_pk_mul_f32 v[16:17], v[48:49], v[16:17]
	s_nop 0
	v_fma_f32 v17, v52, v34, v17
	v_add_f32_e32 v20, v16, v17
	v_and_b32_e32 v17, 0xffff0000, v111
	v_and_b32_e32 v16, 0xffff0000, v115
	v_pk_mul_f32 v[16:17], v[48:49], v[16:17]
	s_nop 0
	v_fma_f32 v17, v52, v35, v17
	v_add_f32_e32 v17, v16, v17
	v_cvt_pk_bf16_f32 v16, v18, v19
	v_cvt_pk_bf16_f32 v17, v20, v17
	v_mov_b32_e32 v236, v16
	v_mov_b32_e32 v237, v17
	v_lshlrev_b32_e32 v17, 16, v112
	v_lshlrev_b32_e32 v16, 16, v116
	v_pk_mul_f32 v[16:17], v[48:49], v[16:17]
	s_nop 0
	v_fma_f32 v17, v52, v36, v17
	v_add_f32_e32 v18, v16, v17
	v_and_b32_e32 v17, 0xffff0000, v112
	v_and_b32_e32 v16, 0xffff0000, v116
	v_pk_mul_f32 v[16:17], v[48:49], v[16:17]
	s_nop 0
	v_fma_f32 v17, v52, v37, v17
	v_add_f32_e32 v19, v16, v17
	v_lshlrev_b32_e32 v17, 16, v113
	v_lshlrev_b32_e32 v16, 16, v117
	v_pk_mul_f32 v[16:17], v[48:49], v[16:17]
	s_nop 0
	v_fma_f32 v17, v52, v38, v17
	v_add_f32_e32 v20, v16, v17
	v_and_b32_e32 v17, 0xffff0000, v113
	v_and_b32_e32 v16, 0xffff0000, v117
	v_pk_mul_f32 v[16:17], v[48:49], v[16:17]
	s_nop 0
	v_fma_f32 v17, v52, v39, v17
	v_add_f32_e32 v17, v16, v17
	v_cvt_pk_bf16_f32 v16, v18, v19
	v_cvt_pk_bf16_f32 v17, v20, v17
	v_mov_b32_e32 v238, v16
	v_mov_b32_e32 v239, v17
	s_nop 1
	v_permlane16_swap_b32 v236, v238
	v_permlane16_swap_b32 v237, v239
	global_store_dwordx4 v[240:241], v[236:239], off offset:128
	v_lshlrev_b32_e32 v17, 16, v118
	v_lshlrev_b32_e32 v16, 16, v122
	v_pk_mul_f32 v[16:17], v[48:49], v[16:17]
	s_nop 0
	v_fma_f32 v17, v52, v40, v17
	v_add_f32_e32 v18, v16, v17
	v_and_b32_e32 v17, 0xffff0000, v118
	v_and_b32_e32 v16, 0xffff0000, v122
	v_pk_mul_f32 v[16:17], v[48:49], v[16:17]
	s_nop 0
	v_fma_f32 v17, v52, v41, v17
	v_add_f32_e32 v19, v16, v17
	v_lshlrev_b32_e32 v17, 16, v119
	v_lshlrev_b32_e32 v16, 16, v123
	v_pk_mul_f32 v[16:17], v[48:49], v[16:17]
	s_nop 0
	v_fma_f32 v17, v52, v42, v17
	v_add_f32_e32 v20, v16, v17
	v_and_b32_e32 v17, 0xffff0000, v119
	v_and_b32_e32 v16, 0xffff0000, v123
	v_pk_mul_f32 v[16:17], v[48:49], v[16:17]
	s_nop 0
	v_fma_f32 v17, v52, v43, v17
	v_add_f32_e32 v17, v16, v17
	v_cvt_pk_bf16_f32 v16, v18, v19
	v_cvt_pk_bf16_f32 v17, v20, v17
	v_mov_b32_e32 v236, v16
	v_mov_b32_e32 v237, v17
	v_lshlrev_b32_e32 v17, 16, v120
	v_lshlrev_b32_e32 v16, 16, v124
	v_pk_mul_f32 v[16:17], v[48:49], v[16:17]
	s_nop 0
	v_fma_f32 v17, v52, v44, v17
	v_add_f32_e32 v18, v16, v17
	v_and_b32_e32 v17, 0xffff0000, v120
	v_and_b32_e32 v16, 0xffff0000, v124
	v_pk_mul_f32 v[16:17], v[48:49], v[16:17]
	s_nop 0
	v_fma_f32 v17, v52, v45, v17
	v_add_f32_e32 v19, v16, v17
	v_lshlrev_b32_e32 v17, 16, v121
	v_lshlrev_b32_e32 v16, 16, v125
	v_pk_mul_f32 v[16:17], v[48:49], v[16:17]
	s_nop 0
	v_fma_f32 v17, v52, v46, v17
	v_add_f32_e32 v20, v16, v17
	v_and_b32_e32 v17, 0xffff0000, v121
	v_and_b32_e32 v16, 0xffff0000, v125
	v_pk_mul_f32 v[16:17], v[48:49], v[16:17]
	s_nop 0
	v_fma_f32 v17, v52, v47, v17
	v_add_f32_e32 v17, v16, v17
	v_cvt_pk_bf16_f32 v16, v18, v19
	v_cvt_pk_bf16_f32 v17, v20, v17
	v_mov_b32_e32 v238, v16
	v_mov_b32_e32 v239, v17
	s_nop 1
	v_permlane16_swap_b32 v236, v238
	v_permlane16_swap_b32 v237, v239
	global_store_dwordx4 v[240:241], v[236:239], off offset:192
	s_cbranch_vccnz .LBB0_538
	s_lshl_b32 s51, s64, 11
	s_cmp_lg_u32 s66, 0
	s_cbranch_scc0 .LBB0_557
	s_lshl_b32 s2, s66, 7
	s_add_i32 s2, s2, s51
	s_add_i32 s50, s2, 0xffffff80
	v_add_u32_e32 v16, s50, v127
	v_ashrrev_i32_e32 v17, 31, v16
	v_lshlrev_b64 v[16:17], 11, v[16:17]
	s_lshl_b32 s48, s34, 7
	v_or_b32_e32 v16, v16, v64
	v_or_b32_e32 v17, v17, v65
	v_or_b32_e32 v16, s48, v16
	v_lshl_add_u64 v[16:17], v[16:17], 1, s[38:39]
	s_add_i32 m0, s57, s35
	s_nop 0
	global_load_lds_dwordx4 v[16:17], off
	v_add_u32_e32 v16, s50, v126
	v_ashrrev_i32_e32 v17, 31, v16
	v_lshlrev_b64 v[16:17], 11, v[16:17]
	v_or_b32_e32 v16, v16, v66
	v_or_b32_e32 v17, v17, v67
	v_or_b32_e32 v16, s48, v16
	v_lshl_add_u64 v[16:17], v[16:17], 1, s[38:39]
	s_add_i32 m0, s57, s54
	s_nop 0
	global_load_lds_dwordx4 v[16:17], off
	v_add_u32_e32 v16, s50, v128
	v_ashrrev_i32_e32 v17, 31, v16
	v_lshlrev_b64 v[16:17], 11, v[16:17]
	v_or_b32_e32 v16, v16, v68
	v_or_b32_e32 v17, v17, v69
	v_or_b32_e32 v16, s48, v16
	v_lshl_add_u64 v[16:17], v[16:17], 1, s[38:39]
	s_add_i32 m0, s57, s55
	s_nop 0
	global_load_lds_dwordx4 v[16:17], off
	v_add_u32_e32 v16, s50, v129
	v_ashrrev_i32_e32 v17, 31, v16
	v_lshlrev_b64 v[16:17], 11, v[16:17]
	v_or_b32_e32 v16, v16, v70
	v_or_b32_e32 v17, v17, v71
	v_or_b32_e32 v16, s48, v16
	v_lshl_add_u64 v[16:17], v[16:17], 1, s[38:39]
	s_add_i32 m0, s57, s56
	s_nop 0
	global_load_lds_dwordx4 v[16:17], off
	s_cbranch_execnz .LBB0_537
	s_branch .LBB0_536
